# attention: lazy softmax rescale (keep reference max while no row max rises by more than 8 in log2 units; exact fallback to the original rescale path)
# speedup vs baseline: 1.0030x; 1.0030x over previous
.LBB0_822:
	s_nop 2
	v_max_f32_e32 v168, v80, v81
	v_max_f32_e32 v169, v64, v65
	v_max3_f32 v168, v168, v82, v83
	v_max3_f32 v169, v169, v66, v67
	v_max3_f32 v168, v168, v84, v85
	v_max3_f32 v169, v169, v68, v69
	v_max3_f32 v168, v168, v86, v87
	v_max3_f32 v169, v169, v70, v71
	v_max3_f32 v168, v168, v88, v89
	v_max3_f32 v169, v169, v72, v73
	v_max3_f32 v168, v168, v90, v91
	v_max3_f32 v169, v169, v74, v75
	v_max3_f32 v168, v168, v92, v93
	v_max3_f32 v169, v169, v76, v77
	v_max3_f32 v168, v168, v94, v95
	v_max3_f32 v169, v169, v78, v79
	v_mov_b32_e32 v170, v168
	v_mov_b32_e32 v171, v169
	s_nop 0
	v_permlane32_swap_b32_e32 v168, v170
	v_permlane32_swap_b32_e32 v169, v171
	v_max3_f32 v168, v159, v168, v170
	v_max3_f32 v169, v158, v169, v171
	v_sub_f32_e32 v168, v168, v159
	v_sub_f32_e32 v169, v169, v158
	v_max_f32_e32 v168, v168, v169
	v_cmp_lt_f32_e32 vcc, 0x41000000, v168
	s_cbranch_vccnz .Latt_slow
	v_sub_f32_e32 v80, v80, v159
	v_sub_f32_e32 v64, v64, v158
	v_sub_f32_e32 v81, v81, v159
	v_sub_f32_e32 v65, v65, v158
	v_sub_f32_e32 v82, v82, v159
	v_sub_f32_e32 v66, v66, v158
	v_sub_f32_e32 v83, v83, v159
	v_sub_f32_e32 v67, v67, v158
	v_sub_f32_e32 v84, v84, v159
	v_sub_f32_e32 v68, v68, v158
	v_sub_f32_e32 v85, v85, v159
	v_sub_f32_e32 v69, v69, v158
	v_sub_f32_e32 v86, v86, v159
	v_sub_f32_e32 v70, v70, v158
	v_sub_f32_e32 v87, v87, v159
	v_sub_f32_e32 v71, v71, v158
	v_sub_f32_e32 v88, v88, v159
	v_sub_f32_e32 v72, v72, v158
	v_sub_f32_e32 v89, v89, v159
	v_sub_f32_e32 v73, v73, v158
	v_sub_f32_e32 v90, v90, v159
	v_sub_f32_e32 v74, v74, v158
	v_sub_f32_e32 v91, v91, v159
	v_sub_f32_e32 v75, v75, v158
	v_sub_f32_e32 v92, v92, v159
	v_sub_f32_e32 v76, v76, v158
	v_sub_f32_e32 v93, v93, v159
	v_sub_f32_e32 v77, v77, v158
	v_sub_f32_e32 v94, v94, v159
	v_sub_f32_e32 v78, v78, v158
	v_sub_f32_e32 v95, v95, v159
	v_sub_f32_e32 v79, v79, v158
	v_exp_f32_e32 v80, v80
	v_exp_f32_e32 v64, v64
	v_exp_f32_e32 v81, v81
	v_exp_f32_e32 v65, v65
	v_exp_f32_e32 v82, v82
	v_exp_f32_e32 v66, v66
	v_exp_f32_e32 v83, v83
	v_exp_f32_e32 v67, v67
	v_exp_f32_e32 v84, v84
	v_exp_f32_e32 v68, v68
	v_exp_f32_e32 v85, v85
	v_exp_f32_e32 v69, v69
	v_exp_f32_e32 v86, v86
	v_exp_f32_e32 v70, v70
	v_exp_f32_e32 v87, v87
	v_exp_f32_e32 v71, v71
	v_exp_f32_e32 v88, v88
	v_exp_f32_e32 v72, v72
	v_exp_f32_e32 v89, v89
	v_exp_f32_e32 v73, v73
	v_exp_f32_e32 v90, v90
	v_exp_f32_e32 v74, v74
	v_exp_f32_e32 v91, v91
	v_exp_f32_e32 v75, v75
	v_exp_f32_e32 v92, v92
	v_exp_f32_e32 v76, v76
	v_exp_f32_e32 v93, v93
	v_exp_f32_e32 v77, v77
	v_exp_f32_e32 v94, v94
	v_exp_f32_e32 v78, v78
	v_exp_f32_e32 v95, v95
	v_exp_f32_e32 v79, v79
	v_add_f32_e32 v168, v80, v81
	v_add_f32_e32 v169, v64, v65
	v_add_f32_e32 v168, v168, v82
	v_add_f32_e32 v169, v169, v66
	v_add_f32_e32 v168, v168, v83
	v_add_f32_e32 v169, v169, v67
	v_add_f32_e32 v168, v168, v84
	v_add_f32_e32 v169, v169, v68
	v_add_f32_e32 v168, v168, v85
	v_add_f32_e32 v169, v169, v69
	v_add_f32_e32 v168, v168, v86
	v_add_f32_e32 v169, v169, v70
	v_add_f32_e32 v168, v168, v87
	v_add_f32_e32 v169, v169, v71
	v_add_f32_e32 v168, v168, v88
	v_add_f32_e32 v169, v169, v72
	v_add_f32_e32 v168, v168, v89
	v_add_f32_e32 v169, v169, v73
	v_add_f32_e32 v168, v168, v90
	v_add_f32_e32 v169, v169, v74
	v_add_f32_e32 v168, v168, v91
	v_add_f32_e32 v169, v169, v75
	v_add_f32_e32 v168, v168, v92
	v_add_f32_e32 v169, v169, v76
	v_add_f32_e32 v168, v168, v93
	v_add_f32_e32 v169, v169, v77
	v_add_f32_e32 v168, v168, v94
	v_add_f32_e32 v169, v169, v78
	v_add_f32_e32 v168, v168, v95
	v_add_f32_e32 v169, v169, v79
	v_add_f32_e32 v149, v149, v168
	v_add_f32_e32 v148, v148, v169
	v_cvt_pk_bf16_f32 v80, v80, v81
	v_cvt_pk_bf16_f32 v81, v82, v83
	v_cvt_pk_bf16_f32 v82, v84, v85
	v_cvt_pk_bf16_f32 v83, v86, v87
	v_cvt_pk_bf16_f32 v84, v88, v89
	v_cvt_pk_bf16_f32 v85, v90, v91
	v_cvt_pk_bf16_f32 v86, v92, v93
	v_cvt_pk_bf16_f32 v87, v94, v95
	v_cvt_pk_bf16_f32 v64, v64, v65
	v_cvt_pk_bf16_f32 v65, v66, v67
	v_cvt_pk_bf16_f32 v66, v68, v69
	v_cvt_pk_bf16_f32 v67, v70, v71
	v_cvt_pk_bf16_f32 v68, v72, v73
	v_cvt_pk_bf16_f32 v69, v74, v75
	v_cvt_pk_bf16_f32 v70, v76, v77
	v_cvt_pk_bf16_f32 v71, v78, v79
	v_mov_b32_e32 v190, v159
	v_mov_b32_e32 v191, v158
	ds_read2_b64 v[72:75], v188 offset1:2
	v_add_u32_e32 v164, 0x2000, v188
	ds_read2_b64 v[76:79], v164 offset0:32 offset1:34
	ds_read2_b64 v[168:171], v188 offset0:4 offset1:6
	ds_read2_b64 v[92:95], v164 offset0:36 offset1:38
	s_branch .Latt_pv
.Latt_slow:
	v_max_f32_e32 v164, v81, v81
	v_max_f32_e32 v165, v80, v80
	v_max_f32_e32 v164, v165, v164
	v_max3_f32 v164, v164, v82, v83
	v_max3_f32 v164, v164, v84, v85
	v_max3_f32 v164, v164, v86, v87
	v_max3_f32 v164, v164, v88, v89
	v_max3_f32 v164, v164, v90, v91
	v_max3_f32 v164, v164, v92, v93
	v_max3_f32 v164, v164, v94, v95
	v_mov_b32_e32 v165, v164
	s_nop 1
	v_permlane32_swap_b32_e32 v164, v165
	v_max3_f32 v190, v159, v164, v165
	v_sub_f32_e32 v80, v80, v190
	v_sub_f32_e32 v81, v81, v190
	v_exp_f32_e32 v80, v80
	v_sub_f32_e32 v82, v82, v190
	v_exp_f32_e32 v81, v81
	v_sub_f32_e32 v83, v83, v190
	v_exp_f32_e32 v82, v82
	v_exp_f32_e32 v83, v83
	v_sub_f32_e32 v84, v84, v190
	v_sub_f32_e32 v164, v159, v190
	v_add_f32_e32 v159, 0, v80
	v_exp_f32_e32 v84, v84
	v_add_f32_e32 v159, v81, v159
	v_add_f32_e32 v159, v82, v159
	v_sub_f32_e32 v85, v85, v190
	v_add_f32_e32 v159, v83, v159
	v_exp_f32_e32 v85, v85
	v_add_f32_e32 v159, v84, v159
	v_cvt_pk_bf16_f32 v80, v80, v81
	v_cvt_pk_bf16_f32 v81, v82, v83
	v_cvt_pk_bf16_f32 v82, v84, v85
	v_max_f32_e32 v83, v65, v65
	v_max_f32_e32 v84, v64, v64
	v_max_f32_e32 v83, v84, v83
	v_max3_f32 v83, v83, v66, v67
	v_max3_f32 v83, v83, v68, v69
	v_max3_f32 v83, v83, v70, v71
	v_sub_f32_e32 v86, v86, v190
	v_max3_f32 v83, v83, v72, v73
	v_exp_f32_e32 v165, v86
	v_sub_f32_e32 v86, v87, v190
	v_max3_f32 v83, v83, v74, v75
	v_exp_f32_e32 v169, v86
	v_sub_f32_e32 v86, v88, v190
	v_max3_f32 v83, v83, v76, v77
	v_add_f32_e32 v193, v85, v159
	v_exp_f32_e32 v159, v86
	v_sub_f32_e32 v86, v89, v190
	v_max3_f32 v88, v83, v78, v79
	v_exp_f32_e32 v89, v86
	v_sub_f32_e32 v86, v90, v190
	v_mov_b32_e32 v90, v88
	v_exp_f32_e32 v167, v86
	v_sub_f32_e32 v86, v91, v190
	v_permlane32_swap_b32_e32 v88, v90
	v_exp_f32_e32 v91, v164
	v_exp_f32_e32 v171, v86
	v_max3_f32 v191, v158, v88, v90
	v_sub_f32_e32 v64, v64, v191
	v_exp_f32_e32 v194, v64
	v_sub_f32_e32 v64, v65, v191
	v_exp_f32_e32 v195, v64
	v_sub_f32_e32 v64, v66, v191
	v_exp_f32_e32 v196, v64
	v_sub_f32_e32 v64, v67, v191
	v_exp_f32_e32 v67, v64
	v_sub_f32_e32 v65, v68, v191
	v_add_f32_e32 v64, 0, v194
	v_exp_f32_e32 v68, v65
	v_sub_f32_e32 v65, v69, v191
	v_add_f32_e32 v64, v195, v64
	v_exp_f32_e32 v69, v65
	v_sub_f32_e32 v65, v70, v191
	v_add_f32_e32 v64, v196, v64
	v_exp_f32_e32 v164, v65
	v_sub_f32_e32 v65, v71, v191
	v_add_f32_e32 v64, v67, v64
	v_exp_f32_e32 v168, v65
	v_sub_f32_e32 v66, v72, v191
	v_sub_f32_e32 v90, v158, v191
	v_add_f32_e32 v64, v68, v64
	v_exp_f32_e32 v158, v66
	v_sub_f32_e32 v66, v73, v191
	v_add_f32_e32 v192, v69, v64
	v_exp_f32_e32 v88, v66
	v_sub_f32_e32 v66, v74, v191
	v_pk_add_f32 v[64:65], v[164:165], v[192:193]
	v_exp_f32_e32 v166, v66
	v_sub_f32_e32 v66, v75, v191
	v_sub_f32_e32 v86, v92, v190
	v_pk_add_f32 v[64:65], v[168:169], v[64:65]
	v_exp_f32_e32 v170, v66
	v_sub_f32_e32 v66, v76, v191
	v_exp_f32_e32 v173, v86
	v_sub_f32_e32 v86, v93, v190
	v_pk_add_f32 v[64:65], v[158:159], v[64:65]
	v_exp_f32_e32 v172, v66
	v_sub_f32_e32 v66, v77, v191
	v_exp_f32_e32 v93, v86
	v_sub_f32_e32 v86, v94, v190
	v_pk_add_f32 v[64:65], v[88:89], v[64:65]
	v_exp_f32_e32 v92, v66
	v_sub_f32_e32 v66, v78, v191
	v_exp_f32_e32 v175, v86
	v_sub_f32_e32 v86, v95, v190
	v_pk_add_f32 v[64:65], v[166:167], v[64:65]
	v_exp_f32_e32 v174, v66
	v_sub_f32_e32 v66, v79, v191
	v_exp_f32_e32 v95, v86
	v_pk_add_f32 v[64:65], v[170:171], v[64:65]
	v_exp_f32_e32 v94, v66
	v_pk_add_f32 v[64:65], v[172:173], v[64:65]
	v_exp_f32_e32 v90, v90
	v_pk_add_f32 v[64:65], v[92:93], v[64:65]
	v_mov_b32_e32 v66, v91
	v_pk_add_f32 v[64:65], v[174:175], v[64:65]
	v_cvt_pk_bf16_f32 v83, v165, v169
	v_cvt_pk_bf16_f32 v84, v159, v89
	v_cvt_pk_bf16_f32 v85, v167, v171
	v_cvt_pk_bf16_f32 v86, v173, v93
	v_cvt_pk_bf16_f32 v87, v175, v95
	s_nop 0
	v_pk_add_f32 v[64:65], v[94:95], v[64:65]
	v_pk_mul_f32 v[46:47], v[46:47], v[66:67] op_sel_hi:[1,0]
	v_pk_mul_f32 v[44:45], v[44:45], v[66:67] op_sel_hi:[1,0]
	v_pk_mul_f32 v[42:43], v[42:43], v[66:67] op_sel_hi:[1,0]
	v_pk_mul_f32 v[40:41], v[40:41], v[66:67] op_sel_hi:[1,0]
	v_pk_mul_f32 v[38:39], v[38:39], v[66:67] op_sel_hi:[1,0]
	v_pk_mul_f32 v[36:37], v[36:37], v[66:67] op_sel_hi:[1,0]
	v_pk_mul_f32 v[34:35], v[34:35], v[66:67] op_sel_hi:[1,0]
	v_pk_mul_f32 v[32:33], v[32:33], v[66:67] op_sel_hi:[1,0]
	v_pk_mul_f32 v[62:63], v[62:63], v[66:67] op_sel_hi:[1,0]
	v_pk_mul_f32 v[60:61], v[60:61], v[66:67] op_sel_hi:[1,0]
	v_pk_mul_f32 v[58:59], v[58:59], v[66:67] op_sel_hi:[1,0]
	v_pk_mul_f32 v[56:57], v[56:57], v[66:67] op_sel_hi:[1,0]
	v_pk_mul_f32 v[54:55], v[54:55], v[66:67] op_sel_hi:[1,0]
	v_pk_mul_f32 v[52:53], v[52:53], v[66:67] op_sel_hi:[1,0]
	v_pk_mul_f32 v[50:51], v[50:51], v[66:67] op_sel_hi:[1,0]
	v_pk_mul_f32 v[48:49], v[48:49], v[66:67] op_sel_hi:[1,0]
	v_pk_fma_f32 v[148:149], v[148:149], v[90:91], v[64:65]
	v_cvt_pk_bf16_f32 v64, v194, v195
	v_cvt_pk_bf16_f32 v65, v196, v67
	v_cvt_pk_bf16_f32 v66, v68, v69
	v_cvt_pk_bf16_f32 v67, v164, v168
	v_cvt_pk_bf16_f32 v68, v158, v88
	v_cvt_pk_bf16_f32 v69, v166, v170
	v_cvt_pk_bf16_f32 v70, v172, v92
	v_cvt_pk_bf16_f32 v71, v174, v94
	ds_read2_b64 v[72:75], v188 offset1:2
	v_add_u32_e32 v164, 0x2000, v188
	ds_read2_b64 v[76:79], v164 offset0:32 offset1:34
	ds_read2_b64 v[168:171], v188 offset0:4 offset1:6
	ds_read2_b64 v[92:95], v164 offset0:36 offset1:38
	v_pk_mul_f32 v[30:31], v[30:31], v[90:91] op_sel_hi:[1,0]
	v_pk_mul_f32 v[28:29], v[28:29], v[90:91] op_sel_hi:[1,0]
	v_pk_mul_f32 v[26:27], v[26:27], v[90:91] op_sel_hi:[1,0]
	v_pk_mul_f32 v[24:25], v[24:25], v[90:91] op_sel_hi:[1,0]
	v_pk_mul_f32 v[22:23], v[22:23], v[90:91] op_sel_hi:[1,0]
	v_pk_mul_f32 v[20:21], v[20:21], v[90:91] op_sel_hi:[1,0]
	v_pk_mul_f32 v[18:19], v[18:19], v[90:91] op_sel_hi:[1,0]
	v_pk_mul_f32 v[16:17], v[16:17], v[90:91] op_sel_hi:[1,0]
	v_pk_mul_f32 v[14:15], v[14:15], v[90:91] op_sel_hi:[1,0]
	v_pk_mul_f32 v[12:13], v[12:13], v[90:91] op_sel_hi:[1,0]
	v_pk_mul_f32 v[10:11], v[10:11], v[90:91] op_sel_hi:[1,0]
	v_pk_mul_f32 v[8:9], v[8:9], v[90:91] op_sel_hi:[1,0]
	v_pk_mul_f32 v[6:7], v[6:7], v[90:91] op_sel_hi:[1,0]
	v_pk_mul_f32 v[4:5], v[4:5], v[90:91] op_sel_hi:[1,0]
	v_pk_mul_f32 v[2:3], v[2:3], v[90:91] op_sel_hi:[1,0]
	v_pk_mul_f32 v[0:1], v[0:1], v[90:91] op_sel_hi:[1,0]
.Latt_pv:
	s_setprio 1
	s_waitcnt lgkmcnt(3)
	v_mfma_f32_32x32x16_bf16 v[32:47], v[72:75], v[80:83], v[32:47]
	v_mfma_f32_32x32x16_bf16 v[16:31], v[72:75], v[64:67], v[16:31]
	s_waitcnt lgkmcnt(2)
	v_mfma_f32_32x32x16_bf16 v[48:63], v[76:79], v[80:83], v[48:63]
	v_mfma_f32_32x32x16_bf16 v[0:15], v[76:79], v[64:67], v[0:15]
	s_waitcnt lgkmcnt(1)
	v_mfma_f32_32x32x16_bf16 v[32:47], v[168:171], v[84:87], v[32:47]
	v_mfma_f32_32x32x16_bf16 v[16:31], v[168:171], v[68:71], v[16:31]
	s_waitcnt lgkmcnt(0)
	v_mfma_f32_32x32x16_bf16 v[48:63], v[92:95], v[84:87], v[48:63]
	v_mfma_f32_32x32x16_bf16 v[0:15], v[92:95], v[68:71], v[0:15]
	s_setprio 0
	s_add_i32 s13, s13, 32
	v_add_u32_e32 v188, 64, v188
	s_cmpk_eq_i32 s13, 0x80
	v_add_u32_e32 v189, 0x1200, v189
	s_cbranch_scc1 .LBB0_824
	v_mov_b32_e32 v158, v191
	v_mov_b32_e32 v159, v190
	s_branch .LBB0_816
